# gate/up epilogue math refactored (act = (g*u)*ri^2*sigmoid(ri*g), row constants hoisted): 9 instead of 12 VALU slots per output pair, all f32
# speedup vs baseline: 1.0032x; 1.0032x over previous
; __device__ __forceinline__ float siluf_(float x) { return x * sigmoidf_(x); }
; __device__ __forceinline__ float rinv_of(float ssq) { return rsqrtf(ssq * (1.0f / 1024.0f) + EPS); }
; __device__ __forceinline__ u32x4 pack8(const f32x4 a, const f32x4 b) { u32x4 w; w.x = cvt_pk_bf16(a[0], a[1]); w.y = cvt_pk_bf16(a[2], a[3]); w.z = cvt_pk_bf16(b[0], b[1]); w.w = cvt_pk_bf16(b[2], b[3]); return w; }
;     __device__ __forceinline__ void operator()(const AccT& acc, const pg8::Unit& u, int wr, int wc, int fr, int fq) const {
;         asm volatile("" : "+v"(fr), "+v"(fq), "+s"(wr), "+s"(wc));
;         float ris[2][4];
; #pragma unroll
;         for (int ai = 0; ai < 2; ++ai)
; #pragma unroll
;             for (int m = 0; m < 4; ++m) ris[ai][m] = ssq_in[EPI_ROW(u, ai, m)];
; #pragma unroll
;         for (int ai = 0; ai < 2; ++ai)
; #pragma unroll
;             for (int m = 0; m < 4; ++m) {
;                 const int r = EPI_ROW(u, ai, m); const float ri = rinv_of(ris[ai][m]);
;                 f32x4 o[2];
; #pragma unroll
;                 for (int n = 0; n < 2; ++n) { const f32x4 gt = acc[ai][0][m][n] * ri, up = acc[ai][1][m][n] * ri;
; #pragma unroll
;                     for (int j = 0; j < 4; ++j) o[n][j] = siluf_(gt[j]) * up[j]; }
;                 *(u32x4*)(act + (size_t)r * DFF + u.pn * 128 + wc * 32 + 8 * fq) = pack8(o[0], o[1]); }
.LBB0_1535:
	s_lshl_b32 s98, s24, 8
	s_lshl_b32 s99, s35, 6
	s_add_i32 s98, s98, s99
	v_add_u32_e32 v160, s98, v148
	v_lshlrev_b32_e32 v168, 2, v160
	s_waitcnt vmcnt(16)
	s_lshl_b32 s98, s25, 7
	s_lshl_b32 s99, s42, 5
	s_add_i32 s98, s98, s99
	v_lshl_add_u32 v161, v149, 3, s98
	v_lshlrev_b32_e32 v161, 1, v161
	v_mul_u32_u24_e32 v169, 0x1600, v160
	v_add_u32_e32 v161, v161, v169
	s_add_u32 s100, s54, 0x9a2dc00
	s_addc_u32 s101, s55, 0
	v_mov_b32_e32 v188, 0x358637bd
	v_fmamk_f32 v162, v248, 0x3a800000, v188
	v_rsq_f32_e32 v162, v162
	v_mov_b32_e32 v168, v161
	s_nop 0
	v_mul_f32_e32 v170, 0xbfb8aa3b, v162
	v_mul_f32_e32 v162, v162, v162
	v_pk_mul_f32 v[164:165], v[116:117], v[170:171] op_sel_hi:[1,0]
	v_pk_mul_f32 v[166:167], v[118:119], v[170:171] op_sel_hi:[1,0]
	v_exp_f32_e32 v164, v164
	v_exp_f32_e32 v165, v165
	v_exp_f32_e32 v166, v166
	v_exp_f32_e32 v167, v167
	v_pk_mul_f32 v[116:117], v[116:117], v[124:125]
	v_pk_mul_f32 v[118:119], v[118:119], v[126:127]
	v_pk_add_f32 v[164:165], v[164:165], 1.0 op_sel_hi:[1,0]
	v_pk_add_f32 v[166:167], v[166:167], 1.0 op_sel_hi:[1,0]
	v_rcp_f32_e32 v164, v164
	v_rcp_f32_e32 v165, v165
	v_rcp_f32_e32 v166, v166
	v_rcp_f32_e32 v167, v167
	v_pk_mul_f32 v[116:117], v[116:117], v[162:163] op_sel_hi:[1,0]
	v_pk_mul_f32 v[118:119], v[118:119], v[162:163] op_sel_hi:[1,0]
	v_pk_mul_f32 v[116:117], v[116:117], v[164:165]
	v_pk_mul_f32 v[118:119], v[118:119], v[166:167]
	v_pk_mul_f32 v[164:165], v[112:113], v[170:171] op_sel_hi:[1,0]
	v_pk_mul_f32 v[166:167], v[114:115], v[170:171] op_sel_hi:[1,0]
	v_exp_f32_e32 v164, v164
	v_exp_f32_e32 v165, v165
	v_exp_f32_e32 v166, v166
	v_exp_f32_e32 v167, v167
	v_pk_mul_f32 v[112:113], v[112:113], v[120:121]
	v_pk_mul_f32 v[114:115], v[114:115], v[122:123]
	v_pk_add_f32 v[164:165], v[164:165], 1.0 op_sel_hi:[1,0]
	v_pk_add_f32 v[166:167], v[166:167], 1.0 op_sel_hi:[1,0]
	v_rcp_f32_e32 v164, v164
	v_rcp_f32_e32 v165, v165
	v_rcp_f32_e32 v166, v166
	v_rcp_f32_e32 v167, v167
	v_pk_mul_f32 v[112:113], v[112:113], v[162:163] op_sel_hi:[1,0]
	v_pk_mul_f32 v[114:115], v[114:115], v[162:163] op_sel_hi:[1,0]
	v_pk_mul_f32 v[112:113], v[112:113], v[164:165]
	v_pk_mul_f32 v[114:115], v[114:115], v[166:167]
	v_cvt_pk_bf16_f32 v172, v116, v117
	v_cvt_pk_bf16_f32 v173, v118, v119
	v_cvt_pk_bf16_f32 v174, v112, v113
	v_cvt_pk_bf16_f32 v175, v114, v115
	global_store_dwordx4 v168, v[172:175], s[100:101]
	v_fmamk_f32 v162, v249, 0x3a800000, v188
	v_rsq_f32_e32 v162, v162
	v_add_u32_e32 v168, 0x16000, v161
	s_nop 0
	v_mul_f32_e32 v170, 0xbfb8aa3b, v162
	v_mul_f32_e32 v162, v162, v162
	v_pk_mul_f32 v[164:165], v[104:105], v[170:171] op_sel_hi:[1,0]
	v_pk_mul_f32 v[166:167], v[106:107], v[170:171] op_sel_hi:[1,0]
	v_exp_f32_e32 v164, v164
	v_exp_f32_e32 v165, v165
	v_exp_f32_e32 v166, v166
	v_exp_f32_e32 v167, v167
	v_pk_mul_f32 v[104:105], v[104:105], v[108:109]
	v_pk_mul_f32 v[106:107], v[106:107], v[110:111]
	v_pk_add_f32 v[164:165], v[164:165], 1.0 op_sel_hi:[1,0]
	v_pk_add_f32 v[166:167], v[166:167], 1.0 op_sel_hi:[1,0]
	v_rcp_f32_e32 v164, v164
	v_rcp_f32_e32 v165, v165
	v_rcp_f32_e32 v166, v166
	v_rcp_f32_e32 v167, v167
	v_pk_mul_f32 v[104:105], v[104:105], v[162:163] op_sel_hi:[1,0]
	v_pk_mul_f32 v[106:107], v[106:107], v[162:163] op_sel_hi:[1,0]
	v_pk_mul_f32 v[104:105], v[104:105], v[164:165]
	v_pk_mul_f32 v[106:107], v[106:107], v[166:167]
	v_pk_mul_f32 v[164:165], v[96:97], v[170:171] op_sel_hi:[1,0]
	v_pk_mul_f32 v[166:167], v[98:99], v[170:171] op_sel_hi:[1,0]
	v_exp_f32_e32 v164, v164
	v_exp_f32_e32 v165, v165
	v_exp_f32_e32 v166, v166
	v_exp_f32_e32 v167, v167
	v_pk_mul_f32 v[96:97], v[96:97], v[100:101]
	v_pk_mul_f32 v[98:99], v[98:99], v[102:103]
	v_pk_add_f32 v[164:165], v[164:165], 1.0 op_sel_hi:[1,0]
	v_pk_add_f32 v[166:167], v[166:167], 1.0 op_sel_hi:[1,0]
	v_rcp_f32_e32 v164, v164
	v_rcp_f32_e32 v165, v165
	v_rcp_f32_e32 v166, v166
	v_rcp_f32_e32 v167, v167
	v_pk_mul_f32 v[96:97], v[96:97], v[162:163] op_sel_hi:[1,0]
	v_pk_mul_f32 v[98:99], v[98:99], v[162:163] op_sel_hi:[1,0]
	v_pk_mul_f32 v[96:97], v[96:97], v[164:165]
	v_pk_mul_f32 v[98:99], v[98:99], v[166:167]
	v_cvt_pk_bf16_f32 v176, v104, v105
	v_cvt_pk_bf16_f32 v177, v106, v107
	v_cvt_pk_bf16_f32 v178, v96, v97
	v_cvt_pk_bf16_f32 v179, v98, v99
	global_store_dwordx4 v168, v[176:179], s[100:101]
	v_fmamk_f32 v162, v250, 0x3a800000, v188
	v_rsq_f32_e32 v162, v162
	v_add_u32_e32 v168, 0x2c000, v161
	s_nop 0
	v_mul_f32_e32 v170, 0xbfb8aa3b, v162
	v_mul_f32_e32 v162, v162, v162
	v_pk_mul_f32 v[164:165], v[88:89], v[170:171] op_sel_hi:[1,0]
	v_pk_mul_f32 v[166:167], v[90:91], v[170:171] op_sel_hi:[1,0]
	v_exp_f32_e32 v164, v164
	v_exp_f32_e32 v165, v165
	v_exp_f32_e32 v166, v166
	v_exp_f32_e32 v167, v167
	v_pk_mul_f32 v[88:89], v[88:89], v[92:93]
	v_pk_mul_f32 v[90:91], v[90:91], v[94:95]
	v_pk_add_f32 v[164:165], v[164:165], 1.0 op_sel_hi:[1,0]
	v_pk_add_f32 v[166:167], v[166:167], 1.0 op_sel_hi:[1,0]
	v_rcp_f32_e32 v164, v164
	v_rcp_f32_e32 v165, v165
	v_rcp_f32_e32 v166, v166
	v_rcp_f32_e32 v167, v167
	v_pk_mul_f32 v[88:89], v[88:89], v[162:163] op_sel_hi:[1,0]
	v_pk_mul_f32 v[90:91], v[90:91], v[162:163] op_sel_hi:[1,0]
	v_pk_mul_f32 v[88:89], v[88:89], v[164:165]
	v_pk_mul_f32 v[90:91], v[90:91], v[166:167]
	v_pk_mul_f32 v[164:165], v[80:81], v[170:171] op_sel_hi:[1,0]
	v_pk_mul_f32 v[166:167], v[82:83], v[170:171] op_sel_hi:[1,0]
	v_exp_f32_e32 v164, v164
	v_exp_f32_e32 v165, v165
	v_exp_f32_e32 v166, v166
	v_exp_f32_e32 v167, v167
	v_pk_mul_f32 v[80:81], v[80:81], v[84:85]
	v_pk_mul_f32 v[82:83], v[82:83], v[86:87]
	v_pk_add_f32 v[164:165], v[164:165], 1.0 op_sel_hi:[1,0]
	v_pk_add_f32 v[166:167], v[166:167], 1.0 op_sel_hi:[1,0]
; __device__ __forceinline__ float siluf_(float x) { return x * sigmoidf_(x); }
; __device__ __forceinline__ float rinv_of(float ssq) { return rsqrtf(ssq * (1.0f / 1024.0f) + EPS); }
; __device__ __forceinline__ u32x4 pack8(const f32x4 a, const f32x4 b) { u32x4 w; w.x = cvt_pk_bf16(a[0], a[1]); w.y = cvt_pk_bf16(a[2], a[3]); w.z = cvt_pk_bf16(b[0], b[1]); w.w = cvt_pk_bf16(b[2], b[3]); return w; }
;     __device__ __forceinline__ void operator()(const AccT& acc, const pg8::Unit& u, int wr, int wc, int fr, int fq) const {
;         asm volatile("" : "+v"(fr), "+v"(fq), "+s"(wr), "+s"(wc));
;         float ris[2][4];
; #pragma unroll
;         for (int ai = 0; ai < 2; ++ai)
; #pragma unroll
;             for (int m = 0; m < 4; ++m) ris[ai][m] = ssq_in[EPI_ROW(u, ai, m)];
; #pragma unroll
;         for (int ai = 0; ai < 2; ++ai)
; #pragma unroll
;             for (int m = 0; m < 4; ++m) {
;                 const int r = EPI_ROW(u, ai, m); const float ri = rinv_of(ris[ai][m]);
;                 f32x4 o[2];
; #pragma unroll
;                 for (int n = 0; n < 2; ++n) { const f32x4 gt = acc[ai][0][m][n] * ri, up = acc[ai][1][m][n] * ri;
; #pragma unroll
;                     for (int j = 0; j < 4; ++j) o[n][j] = siluf_(gt[j]) * up[j]; }
;                 *(u32x4*)(act + (size_t)r * DFF + u.pn * 128 + wc * 32 + 8 * fq) = pack8(o[0], o[1]); }
	v_rcp_f32_e32 v164, v164
	v_rcp_f32_e32 v165, v165
	v_rcp_f32_e32 v166, v166
	v_rcp_f32_e32 v167, v167
	v_pk_mul_f32 v[80:81], v[80:81], v[162:163] op_sel_hi:[1,0]
	v_pk_mul_f32 v[82:83], v[82:83], v[162:163] op_sel_hi:[1,0]
	v_pk_mul_f32 v[80:81], v[80:81], v[164:165]
	v_pk_mul_f32 v[82:83], v[82:83], v[166:167]
	v_cvt_pk_bf16_f32 v172, v88, v89
	v_cvt_pk_bf16_f32 v173, v90, v91
	v_cvt_pk_bf16_f32 v174, v80, v81
	v_cvt_pk_bf16_f32 v175, v82, v83
	global_store_dwordx4 v168, v[172:175], s[100:101]
	v_fmamk_f32 v162, v251, 0x3a800000, v188
	v_rsq_f32_e32 v162, v162
	v_add_u32_e32 v168, 0x42000, v161
	s_nop 0
	v_mul_f32_e32 v170, 0xbfb8aa3b, v162
	v_mul_f32_e32 v162, v162, v162
	v_pk_mul_f32 v[164:165], v[72:73], v[170:171] op_sel_hi:[1,0]
	v_pk_mul_f32 v[166:167], v[74:75], v[170:171] op_sel_hi:[1,0]
	v_exp_f32_e32 v164, v164
	v_exp_f32_e32 v165, v165
	v_exp_f32_e32 v166, v166
	v_exp_f32_e32 v167, v167
	v_pk_mul_f32 v[72:73], v[72:73], v[76:77]
	v_pk_mul_f32 v[74:75], v[74:75], v[78:79]
	v_pk_add_f32 v[164:165], v[164:165], 1.0 op_sel_hi:[1,0]
	v_pk_add_f32 v[166:167], v[166:167], 1.0 op_sel_hi:[1,0]
	v_rcp_f32_e32 v164, v164
	v_rcp_f32_e32 v165, v165
	v_rcp_f32_e32 v166, v166
	v_rcp_f32_e32 v167, v167
	v_pk_mul_f32 v[72:73], v[72:73], v[162:163] op_sel_hi:[1,0]
	v_pk_mul_f32 v[74:75], v[74:75], v[162:163] op_sel_hi:[1,0]
	v_pk_mul_f32 v[72:73], v[72:73], v[164:165]
	v_pk_mul_f32 v[74:75], v[74:75], v[166:167]
	v_pk_mul_f32 v[164:165], v[64:65], v[170:171] op_sel_hi:[1,0]
	v_pk_mul_f32 v[166:167], v[66:67], v[170:171] op_sel_hi:[1,0]
	v_exp_f32_e32 v164, v164
	v_exp_f32_e32 v165, v165
	v_exp_f32_e32 v166, v166
	v_exp_f32_e32 v167, v167
	v_pk_mul_f32 v[64:65], v[64:65], v[68:69]
	v_pk_mul_f32 v[66:67], v[66:67], v[70:71]
	v_pk_add_f32 v[164:165], v[164:165], 1.0 op_sel_hi:[1,0]
	v_pk_add_f32 v[166:167], v[166:167], 1.0 op_sel_hi:[1,0]
	v_rcp_f32_e32 v164, v164
	v_rcp_f32_e32 v165, v165
	v_rcp_f32_e32 v166, v166
	v_rcp_f32_e32 v167, v167
	v_pk_mul_f32 v[64:65], v[64:65], v[162:163] op_sel_hi:[1,0]
	v_pk_mul_f32 v[66:67], v[66:67], v[162:163] op_sel_hi:[1,0]
	v_pk_mul_f32 v[64:65], v[64:65], v[164:165]
	v_pk_mul_f32 v[66:67], v[66:67], v[166:167]
	v_cvt_pk_bf16_f32 v176, v72, v73
	v_cvt_pk_bf16_f32 v177, v74, v75
	v_cvt_pk_bf16_f32 v178, v64, v65
	v_cvt_pk_bf16_f32 v179, v66, v67
	global_store_dwordx4 v168, v[176:179], s[100:101]
	v_fmamk_f32 v162, v252, 0x3a800000, v188
	v_rsq_f32_e32 v162, v162
	v_add_u32_e32 v168, 0xb0000, v161
	s_nop 0
	v_mul_f32_e32 v170, 0xbfb8aa3b, v162
	v_mul_f32_e32 v162, v162, v162
	v_pk_mul_f32 v[164:165], v[56:57], v[170:171] op_sel_hi:[1,0]
	v_pk_mul_f32 v[166:167], v[58:59], v[170:171] op_sel_hi:[1,0]
	v_exp_f32_e32 v164, v164
	v_exp_f32_e32 v165, v165
	v_exp_f32_e32 v166, v166
	v_exp_f32_e32 v167, v167
	v_pk_mul_f32 v[56:57], v[56:57], v[60:61]
	v_pk_mul_f32 v[58:59], v[58:59], v[62:63]
	v_pk_add_f32 v[164:165], v[164:165], 1.0 op_sel_hi:[1,0]
	v_pk_add_f32 v[166:167], v[166:167], 1.0 op_sel_hi:[1,0]
	v_rcp_f32_e32 v164, v164
	v_rcp_f32_e32 v165, v165
	v_rcp_f32_e32 v166, v166
	v_rcp_f32_e32 v167, v167
	v_pk_mul_f32 v[56:57], v[56:57], v[162:163] op_sel_hi:[1,0]
	v_pk_mul_f32 v[58:59], v[58:59], v[162:163] op_sel_hi:[1,0]
	v_pk_mul_f32 v[56:57], v[56:57], v[164:165]
	v_pk_mul_f32 v[58:59], v[58:59], v[166:167]
	v_pk_mul_f32 v[164:165], v[48:49], v[170:171] op_sel_hi:[1,0]
	v_pk_mul_f32 v[166:167], v[50:51], v[170:171] op_sel_hi:[1,0]
	v_exp_f32_e32 v164, v164
	v_exp_f32_e32 v165, v165
	v_exp_f32_e32 v166, v166
	v_exp_f32_e32 v167, v167
	v_pk_mul_f32 v[48:49], v[48:49], v[52:53]
	v_pk_mul_f32 v[50:51], v[50:51], v[54:55]
	v_pk_add_f32 v[164:165], v[164:165], 1.0 op_sel_hi:[1,0]
	v_pk_add_f32 v[166:167], v[166:167], 1.0 op_sel_hi:[1,0]
	v_rcp_f32_e32 v164, v164
	v_rcp_f32_e32 v165, v165
	v_rcp_f32_e32 v166, v166
	v_rcp_f32_e32 v167, v167
	v_pk_mul_f32 v[48:49], v[48:49], v[162:163] op_sel_hi:[1,0]
	v_pk_mul_f32 v[50:51], v[50:51], v[162:163] op_sel_hi:[1,0]
	v_pk_mul_f32 v[48:49], v[48:49], v[164:165]
	v_pk_mul_f32 v[50:51], v[50:51], v[166:167]
	v_cvt_pk_bf16_f32 v172, v56, v57
	v_cvt_pk_bf16_f32 v173, v58, v59
	v_cvt_pk_bf16_f32 v174, v48, v49
	v_cvt_pk_bf16_f32 v175, v50, v51
	global_store_dwordx4 v168, v[172:175], s[100:101]
	v_fmamk_f32 v162, v253, 0x3a800000, v188
	v_rsq_f32_e32 v162, v162
	v_add_u32_e32 v168, 0xc6000, v161
	s_nop 0
	v_mul_f32_e32 v170, 0xbfb8aa3b, v162
	v_mul_f32_e32 v162, v162, v162
	v_pk_mul_f32 v[164:165], v[40:41], v[170:171] op_sel_hi:[1,0]
	v_pk_mul_f32 v[166:167], v[42:43], v[170:171] op_sel_hi:[1,0]
	v_exp_f32_e32 v164, v164
	v_exp_f32_e32 v165, v165
	v_exp_f32_e32 v166, v166
	v_exp_f32_e32 v167, v167
	v_pk_mul_f32 v[40:41], v[40:41], v[44:45]
	v_pk_mul_f32 v[42:43], v[42:43], v[46:47]
	v_pk_add_f32 v[164:165], v[164:165], 1.0 op_sel_hi:[1,0]
	v_pk_add_f32 v[166:167], v[166:167], 1.0 op_sel_hi:[1,0]
	v_rcp_f32_e32 v164, v164
	v_rcp_f32_e32 v165, v165
	v_rcp_f32_e32 v166, v166
	v_rcp_f32_e32 v167, v167
; __device__ __forceinline__ float siluf_(float x) { return x * sigmoidf_(x); }
; __device__ __forceinline__ float rinv_of(float ssq) { return rsqrtf(ssq * (1.0f / 1024.0f) + EPS); }
; __device__ __forceinline__ u32x4 pack8(const f32x4 a, const f32x4 b) { u32x4 w; w.x = cvt_pk_bf16(a[0], a[1]); w.y = cvt_pk_bf16(a[2], a[3]); w.z = cvt_pk_bf16(b[0], b[1]); w.w = cvt_pk_bf16(b[2], b[3]); return w; }
;     __device__ __forceinline__ void operator()(const AccT& acc, const pg8::Unit& u, int wr, int wc, int fr, int fq) const {
;         asm volatile("" : "+v"(fr), "+v"(fq), "+s"(wr), "+s"(wc));
;         float ris[2][4];
; #pragma unroll
;         for (int ai = 0; ai < 2; ++ai)
; #pragma unroll
;             for (int m = 0; m < 4; ++m) ris[ai][m] = ssq_in[EPI_ROW(u, ai, m)];
; #pragma unroll
;         for (int ai = 0; ai < 2; ++ai)
; #pragma unroll
;             for (int m = 0; m < 4; ++m) {
;                 const int r = EPI_ROW(u, ai, m); const float ri = rinv_of(ris[ai][m]);
;                 f32x4 o[2];
; #pragma unroll
;                 for (int n = 0; n < 2; ++n) { const f32x4 gt = acc[ai][0][m][n] * ri, up = acc[ai][1][m][n] * ri;
; #pragma unroll
;                     for (int j = 0; j < 4; ++j) o[n][j] = siluf_(gt[j]) * up[j]; }
;                 *(u32x4*)(act + (size_t)r * DFF + u.pn * 128 + wc * 32 + 8 * fq) = pack8(o[0], o[1]); }
	v_pk_mul_f32 v[40:41], v[40:41], v[162:163] op_sel_hi:[1,0]
	v_pk_mul_f32 v[42:43], v[42:43], v[162:163] op_sel_hi:[1,0]
	v_pk_mul_f32 v[40:41], v[40:41], v[164:165]
	v_pk_mul_f32 v[42:43], v[42:43], v[166:167]
	v_pk_mul_f32 v[164:165], v[32:33], v[170:171] op_sel_hi:[1,0]
	v_pk_mul_f32 v[166:167], v[34:35], v[170:171] op_sel_hi:[1,0]
	v_exp_f32_e32 v164, v164
	v_exp_f32_e32 v165, v165
	v_exp_f32_e32 v166, v166
	v_exp_f32_e32 v167, v167
	v_pk_mul_f32 v[32:33], v[32:33], v[36:37]
	v_pk_mul_f32 v[34:35], v[34:35], v[38:39]
	v_pk_add_f32 v[164:165], v[164:165], 1.0 op_sel_hi:[1,0]
	v_pk_add_f32 v[166:167], v[166:167], 1.0 op_sel_hi:[1,0]
	v_rcp_f32_e32 v164, v164
	v_rcp_f32_e32 v165, v165
	v_rcp_f32_e32 v166, v166
	v_rcp_f32_e32 v167, v167
	v_pk_mul_f32 v[32:33], v[32:33], v[162:163] op_sel_hi:[1,0]
	v_pk_mul_f32 v[34:35], v[34:35], v[162:163] op_sel_hi:[1,0]
	v_pk_mul_f32 v[32:33], v[32:33], v[164:165]
	v_pk_mul_f32 v[34:35], v[34:35], v[166:167]
	v_cvt_pk_bf16_f32 v176, v40, v41
	v_cvt_pk_bf16_f32 v177, v42, v43
	v_cvt_pk_bf16_f32 v178, v32, v33
	v_cvt_pk_bf16_f32 v179, v34, v35
	global_store_dwordx4 v168, v[176:179], s[100:101]
	v_fmamk_f32 v162, v254, 0x3a800000, v188
	v_rsq_f32_e32 v162, v162
	v_add_u32_e32 v168, 0xdc000, v161
	s_nop 0
	v_mul_f32_e32 v170, 0xbfb8aa3b, v162
	v_mul_f32_e32 v162, v162, v162
	v_pk_mul_f32 v[164:165], v[24:25], v[170:171] op_sel_hi:[1,0]
	v_pk_mul_f32 v[166:167], v[26:27], v[170:171] op_sel_hi:[1,0]
	v_exp_f32_e32 v164, v164
	v_exp_f32_e32 v165, v165
	v_exp_f32_e32 v166, v166
	v_exp_f32_e32 v167, v167
	v_pk_mul_f32 v[24:25], v[24:25], v[28:29]
	v_pk_mul_f32 v[26:27], v[26:27], v[30:31]
	v_pk_add_f32 v[164:165], v[164:165], 1.0 op_sel_hi:[1,0]
	v_pk_add_f32 v[166:167], v[166:167], 1.0 op_sel_hi:[1,0]
	v_rcp_f32_e32 v164, v164
	v_rcp_f32_e32 v165, v165
	v_rcp_f32_e32 v166, v166
	v_rcp_f32_e32 v167, v167
	v_pk_mul_f32 v[24:25], v[24:25], v[162:163] op_sel_hi:[1,0]
	v_pk_mul_f32 v[26:27], v[26:27], v[162:163] op_sel_hi:[1,0]
	v_pk_mul_f32 v[24:25], v[24:25], v[164:165]
	v_pk_mul_f32 v[26:27], v[26:27], v[166:167]
	v_pk_mul_f32 v[164:165], v[16:17], v[170:171] op_sel_hi:[1,0]
	v_pk_mul_f32 v[166:167], v[18:19], v[170:171] op_sel_hi:[1,0]
	v_exp_f32_e32 v164, v164
	v_exp_f32_e32 v165, v165
	v_exp_f32_e32 v166, v166
	v_exp_f32_e32 v167, v167
	v_pk_mul_f32 v[16:17], v[16:17], v[20:21]
	v_pk_mul_f32 v[18:19], v[18:19], v[22:23]
	v_pk_add_f32 v[164:165], v[164:165], 1.0 op_sel_hi:[1,0]
	v_pk_add_f32 v[166:167], v[166:167], 1.0 op_sel_hi:[1,0]
	v_rcp_f32_e32 v164, v164
	v_rcp_f32_e32 v165, v165
	v_rcp_f32_e32 v166, v166
	v_rcp_f32_e32 v167, v167
	v_pk_mul_f32 v[16:17], v[16:17], v[162:163] op_sel_hi:[1,0]
	v_pk_mul_f32 v[18:19], v[18:19], v[162:163] op_sel_hi:[1,0]
	v_pk_mul_f32 v[16:17], v[16:17], v[164:165]
	v_pk_mul_f32 v[18:19], v[18:19], v[166:167]
	v_cvt_pk_bf16_f32 v172, v24, v25
	v_cvt_pk_bf16_f32 v173, v26, v27
	v_cvt_pk_bf16_f32 v174, v16, v17
	v_cvt_pk_bf16_f32 v175, v18, v19
	global_store_dwordx4 v168, v[172:175], s[100:101]
	v_fmamk_f32 v162, v255, 0x3a800000, v188
	v_rsq_f32_e32 v162, v162
	v_add_u32_e32 v168, 0xf2000, v161
	s_nop 0
	v_mul_f32_e32 v170, 0xbfb8aa3b, v162
	v_mul_f32_e32 v162, v162, v162
	v_pk_mul_f32 v[164:165], v[8:9], v[170:171] op_sel_hi:[1,0]
	v_pk_mul_f32 v[166:167], v[10:11], v[170:171] op_sel_hi:[1,0]
	v_exp_f32_e32 v164, v164
	v_exp_f32_e32 v165, v165
	v_exp_f32_e32 v166, v166
	v_exp_f32_e32 v167, v167
	v_pk_mul_f32 v[8:9], v[8:9], v[12:13]
	v_pk_mul_f32 v[10:11], v[10:11], v[14:15]
	v_pk_add_f32 v[164:165], v[164:165], 1.0 op_sel_hi:[1,0]
	v_pk_add_f32 v[166:167], v[166:167], 1.0 op_sel_hi:[1,0]
	v_rcp_f32_e32 v164, v164
	v_rcp_f32_e32 v165, v165
	v_rcp_f32_e32 v166, v166
	v_rcp_f32_e32 v167, v167
	v_pk_mul_f32 v[8:9], v[8:9], v[162:163] op_sel_hi:[1,0]
	v_pk_mul_f32 v[10:11], v[10:11], v[162:163] op_sel_hi:[1,0]
	v_pk_mul_f32 v[8:9], v[8:9], v[164:165]
	v_pk_mul_f32 v[10:11], v[10:11], v[166:167]
	v_pk_mul_f32 v[164:165], v[4:5], v[170:171] op_sel_hi:[1,0]
	v_pk_mul_f32 v[166:167], v[6:7], v[170:171] op_sel_hi:[1,0]
	v_exp_f32_e32 v164, v164
	v_exp_f32_e32 v165, v165
	v_exp_f32_e32 v166, v166
	v_exp_f32_e32 v167, v167
	v_pk_mul_f32 v[4:5], v[4:5], v[0:1]
	v_pk_mul_f32 v[6:7], v[6:7], v[2:3]
	v_pk_add_f32 v[164:165], v[164:165], 1.0 op_sel_hi:[1,0]
	v_pk_add_f32 v[166:167], v[166:167], 1.0 op_sel_hi:[1,0]
	v_rcp_f32_e32 v164, v164
	v_rcp_f32_e32 v165, v165
	v_rcp_f32_e32 v166, v166
	v_rcp_f32_e32 v167, v167
	v_pk_mul_f32 v[4:5], v[4:5], v[162:163] op_sel_hi:[1,0]
	v_pk_mul_f32 v[6:7], v[6:7], v[162:163] op_sel_hi:[1,0]
	v_pk_mul_f32 v[4:5], v[4:5], v[164:165]
	v_pk_mul_f32 v[6:7], v[6:7], v[166:167]
	v_cvt_pk_bf16_f32 v176, v8, v9
	v_cvt_pk_bf16_f32 v177, v10, v11
	v_cvt_pk_bf16_f32 v178, v4, v5
	v_cvt_pk_bf16_f32 v179, v6, v7
	global_store_dwordx4 v168, v[176:179], s[100:101]
	s_mov_b64 s[28:29], s[18:19]
	s_mov_b32 s25, s14
	s_mov_b32 s24, s16
	s_mov_b64 s[26:27], s[22:23]
	s_and_b64 vcc, exec, s[6:7]
	s_cbranch_vccnz .LBB0_1545

; __device__ __forceinline__ float siluf_(float x) { return x * sigmoidf_(x); }
; __device__ __forceinline__ float rinv_of(float ssq) { return rsqrtf(ssq * (1.0f / 1024.0f) + EPS); }
; __device__ __forceinline__ u32x4 pack8(const f32x4 a, const f32x4 b) { u32x4 w; w.x = cvt_pk_bf16(a[0], a[1]); w.y = cvt_pk_bf16(a[2], a[3]); w.z = cvt_pk_bf16(b[0], b[1]); w.w = cvt_pk_bf16(b[2], b[3]); return w; }
;     __device__ __forceinline__ void operator()(const AccT& acc, const pg8::Unit& u, int wr, int wc, int fr, int fq) const {
;         asm volatile("" : "+v"(fr), "+v"(fq), "+s"(wr), "+s"(wc));
;         float ris[2][4];
; #pragma unroll
;         for (int ai = 0; ai < 2; ++ai)
; #pragma unroll
;             for (int m = 0; m < 4; ++m) ris[ai][m] = ssq_in[EPI_ROW(u, ai, m)];
; #pragma unroll
;         for (int ai = 0; ai < 2; ++ai)
; #pragma unroll
;             for (int m = 0; m < 4; ++m) {
;                 const int r = EPI_ROW(u, ai, m); const float ri = rinv_of(ris[ai][m]);
;                 f32x4 o[2];
; #pragma unroll
;                 for (int n = 0; n < 2; ++n) { const f32x4 gt = acc[ai][0][m][n] * ri, up = acc[ai][1][m][n] * ri;
; #pragma unroll
;                     for (int j = 0; j < 4; ++j) o[n][j] = siluf_(gt[j]) * up[j]; }
;                 *(u32x4*)(act + (size_t)r * DFF + u.pn * 128 + wc * 32 + 8 * fq) = pack8(o[0], o[1]); }
;     }
.LBB0_2402:
	s_lshl_b32 s98, s24, 8
	s_lshl_b32 s99, s35, 6
	s_add_i32 s98, s98, s99
	v_add_u32_e32 v160, s98, v148
	v_lshlrev_b32_e32 v168, 2, v160
	s_waitcnt vmcnt(16)
	s_lshl_b32 s98, s25, 7
	s_lshl_b32 s99, s42, 5
	s_add_i32 s98, s98, s99
	v_lshl_add_u32 v161, v149, 3, s98
	v_lshlrev_b32_e32 v161, 1, v161
	v_mul_u32_u24_e32 v169, 0x1600, v160
	v_add_u32_e32 v161, v161, v169
	s_add_u32 s100, s54, 0x9a2dc00
	s_addc_u32 s101, s55, 0
	v_mov_b32_e32 v188, 0x358637bd
	v_fmamk_f32 v162, v248, 0x3a800000, v188
	v_rsq_f32_e32 v162, v162
	v_mov_b32_e32 v168, v161
	s_nop 0
	v_mul_f32_e32 v170, 0xbfb8aa3b, v162
	v_mul_f32_e32 v162, v162, v162
	v_pk_mul_f32 v[164:165], v[116:117], v[170:171] op_sel_hi:[1,0]
	v_pk_mul_f32 v[166:167], v[118:119], v[170:171] op_sel_hi:[1,0]
	v_exp_f32_e32 v164, v164
	v_exp_f32_e32 v165, v165
	v_exp_f32_e32 v166, v166
	v_exp_f32_e32 v167, v167
	v_pk_mul_f32 v[116:117], v[116:117], v[124:125]
	v_pk_mul_f32 v[118:119], v[118:119], v[126:127]
	v_pk_add_f32 v[164:165], v[164:165], 1.0 op_sel_hi:[1,0]
	v_pk_add_f32 v[166:167], v[166:167], 1.0 op_sel_hi:[1,0]
	v_rcp_f32_e32 v164, v164
	v_rcp_f32_e32 v165, v165
	v_rcp_f32_e32 v166, v166
	v_rcp_f32_e32 v167, v167
	v_pk_mul_f32 v[116:117], v[116:117], v[162:163] op_sel_hi:[1,0]
	v_pk_mul_f32 v[118:119], v[118:119], v[162:163] op_sel_hi:[1,0]
	v_pk_mul_f32 v[116:117], v[116:117], v[164:165]
	v_pk_mul_f32 v[118:119], v[118:119], v[166:167]
	v_pk_mul_f32 v[164:165], v[112:113], v[170:171] op_sel_hi:[1,0]
	v_pk_mul_f32 v[166:167], v[114:115], v[170:171] op_sel_hi:[1,0]
	v_exp_f32_e32 v164, v164
	v_exp_f32_e32 v165, v165
	v_exp_f32_e32 v166, v166
	v_exp_f32_e32 v167, v167
	v_pk_mul_f32 v[112:113], v[112:113], v[120:121]
	v_pk_mul_f32 v[114:115], v[114:115], v[122:123]
	v_pk_add_f32 v[164:165], v[164:165], 1.0 op_sel_hi:[1,0]
	v_pk_add_f32 v[166:167], v[166:167], 1.0 op_sel_hi:[1,0]
	v_rcp_f32_e32 v164, v164
	v_rcp_f32_e32 v165, v165
	v_rcp_f32_e32 v166, v166
	v_rcp_f32_e32 v167, v167
	v_pk_mul_f32 v[112:113], v[112:113], v[162:163] op_sel_hi:[1,0]
	v_pk_mul_f32 v[114:115], v[114:115], v[162:163] op_sel_hi:[1,0]
	v_pk_mul_f32 v[112:113], v[112:113], v[164:165]
	v_pk_mul_f32 v[114:115], v[114:115], v[166:167]
	v_cvt_pk_bf16_f32 v172, v116, v117
	v_cvt_pk_bf16_f32 v173, v118, v119
	v_cvt_pk_bf16_f32 v174, v112, v113
	v_cvt_pk_bf16_f32 v175, v114, v115
	global_store_dwordx4 v168, v[172:175], s[100:101]
	v_fmamk_f32 v162, v249, 0x3a800000, v188
	v_rsq_f32_e32 v162, v162
	v_add_u32_e32 v168, 0x16000, v161
	s_nop 0
	v_mul_f32_e32 v170, 0xbfb8aa3b, v162
	v_mul_f32_e32 v162, v162, v162
	v_pk_mul_f32 v[164:165], v[104:105], v[170:171] op_sel_hi:[1,0]
	v_pk_mul_f32 v[166:167], v[106:107], v[170:171] op_sel_hi:[1,0]
	v_exp_f32_e32 v164, v164
	v_exp_f32_e32 v165, v165
	v_exp_f32_e32 v166, v166
	v_exp_f32_e32 v167, v167
	v_pk_mul_f32 v[104:105], v[104:105], v[108:109]
	v_pk_mul_f32 v[106:107], v[106:107], v[110:111]
	v_pk_add_f32 v[164:165], v[164:165], 1.0 op_sel_hi:[1,0]
	v_pk_add_f32 v[166:167], v[166:167], 1.0 op_sel_hi:[1,0]
	v_rcp_f32_e32 v164, v164
	v_rcp_f32_e32 v165, v165
	v_rcp_f32_e32 v166, v166
	v_rcp_f32_e32 v167, v167
	v_pk_mul_f32 v[104:105], v[104:105], v[162:163] op_sel_hi:[1,0]
	v_pk_mul_f32 v[106:107], v[106:107], v[162:163] op_sel_hi:[1,0]
	v_pk_mul_f32 v[104:105], v[104:105], v[164:165]
	v_pk_mul_f32 v[106:107], v[106:107], v[166:167]
	v_pk_mul_f32 v[164:165], v[96:97], v[170:171] op_sel_hi:[1,0]
	v_pk_mul_f32 v[166:167], v[98:99], v[170:171] op_sel_hi:[1,0]
	v_exp_f32_e32 v164, v164
	v_exp_f32_e32 v165, v165
	v_exp_f32_e32 v166, v166
	v_exp_f32_e32 v167, v167
	v_pk_mul_f32 v[96:97], v[96:97], v[100:101]
	v_pk_mul_f32 v[98:99], v[98:99], v[102:103]
	v_pk_add_f32 v[164:165], v[164:165], 1.0 op_sel_hi:[1,0]
	v_pk_add_f32 v[166:167], v[166:167], 1.0 op_sel_hi:[1,0]
	v_rcp_f32_e32 v164, v164
	v_rcp_f32_e32 v165, v165
	v_rcp_f32_e32 v166, v166
	v_rcp_f32_e32 v167, v167
	v_pk_mul_f32 v[96:97], v[96:97], v[162:163] op_sel_hi:[1,0]
	v_pk_mul_f32 v[98:99], v[98:99], v[162:163] op_sel_hi:[1,0]
	v_pk_mul_f32 v[96:97], v[96:97], v[164:165]
	v_pk_mul_f32 v[98:99], v[98:99], v[166:167]
	v_cvt_pk_bf16_f32 v176, v104, v105
	v_cvt_pk_bf16_f32 v177, v106, v107
	v_cvt_pk_bf16_f32 v178, v96, v97
	v_cvt_pk_bf16_f32 v179, v98, v99
	global_store_dwordx4 v168, v[176:179], s[100:101]
	v_fmamk_f32 v162, v250, 0x3a800000, v188
	v_rsq_f32_e32 v162, v162
	v_add_u32_e32 v168, 0x2c000, v161
	s_nop 0
	v_mul_f32_e32 v170, 0xbfb8aa3b, v162
	v_mul_f32_e32 v162, v162, v162
	v_pk_mul_f32 v[164:165], v[88:89], v[170:171] op_sel_hi:[1,0]
	v_pk_mul_f32 v[166:167], v[90:91], v[170:171] op_sel_hi:[1,0]
	v_exp_f32_e32 v164, v164
	v_exp_f32_e32 v165, v165
	v_exp_f32_e32 v166, v166
	v_exp_f32_e32 v167, v167
	v_pk_mul_f32 v[88:89], v[88:89], v[92:93]
	v_pk_mul_f32 v[90:91], v[90:91], v[94:95]
	v_pk_add_f32 v[164:165], v[164:165], 1.0 op_sel_hi:[1,0]
	v_pk_add_f32 v[166:167], v[166:167], 1.0 op_sel_hi:[1,0]
	v_rcp_f32_e32 v164, v164
	v_rcp_f32_e32 v165, v165
	v_rcp_f32_e32 v166, v166
	v_rcp_f32_e32 v167, v167
	v_pk_mul_f32 v[88:89], v[88:89], v[162:163] op_sel_hi:[1,0]
	v_pk_mul_f32 v[90:91], v[90:91], v[162:163] op_sel_hi:[1,0]
	v_pk_mul_f32 v[88:89], v[88:89], v[164:165]
	v_pk_mul_f32 v[90:91], v[90:91], v[166:167]
	v_pk_mul_f32 v[164:165], v[80:81], v[170:171] op_sel_hi:[1,0]
	v_pk_mul_f32 v[166:167], v[82:83], v[170:171] op_sel_hi:[1,0]
	v_exp_f32_e32 v164, v164
	v_exp_f32_e32 v165, v165
	v_exp_f32_e32 v166, v166
	v_exp_f32_e32 v167, v167
	v_pk_mul_f32 v[80:81], v[80:81], v[84:85]
	v_pk_mul_f32 v[82:83], v[82:83], v[86:87]
	v_pk_add_f32 v[164:165], v[164:165], 1.0 op_sel_hi:[1,0]
	v_pk_add_f32 v[166:167], v[166:167], 1.0 op_sel_hi:[1,0]
; __device__ __forceinline__ float siluf_(float x) { return x * sigmoidf_(x); }
; __device__ __forceinline__ float rinv_of(float ssq) { return rsqrtf(ssq * (1.0f / 1024.0f) + EPS); }
; __device__ __forceinline__ u32x4 pack8(const f32x4 a, const f32x4 b) { u32x4 w; w.x = cvt_pk_bf16(a[0], a[1]); w.y = cvt_pk_bf16(a[2], a[3]); w.z = cvt_pk_bf16(b[0], b[1]); w.w = cvt_pk_bf16(b[2], b[3]); return w; }
;     __device__ __forceinline__ void operator()(const AccT& acc, const pg8::Unit& u, int wr, int wc, int fr, int fq) const {
;         asm volatile("" : "+v"(fr), "+v"(fq), "+s"(wr), "+s"(wc));
;         float ris[2][4];
; #pragma unroll
;         for (int ai = 0; ai < 2; ++ai)
; #pragma unroll
;             for (int m = 0; m < 4; ++m) ris[ai][m] = ssq_in[EPI_ROW(u, ai, m)];
; #pragma unroll
;         for (int ai = 0; ai < 2; ++ai)
; #pragma unroll
;             for (int m = 0; m < 4; ++m) {
;                 const int r = EPI_ROW(u, ai, m); const float ri = rinv_of(ris[ai][m]);
;                 f32x4 o[2];
; #pragma unroll
;                 for (int n = 0; n < 2; ++n) { const f32x4 gt = acc[ai][0][m][n] * ri, up = acc[ai][1][m][n] * ri;
; #pragma unroll
;                     for (int j = 0; j < 4; ++j) o[n][j] = siluf_(gt[j]) * up[j]; }
;                 *(u32x4*)(act + (size_t)r * DFF + u.pn * 128 + wc * 32 + 8 * fq) = pack8(o[0], o[1]); }
;     }
	v_rcp_f32_e32 v164, v164
	v_rcp_f32_e32 v165, v165
	v_rcp_f32_e32 v166, v166
	v_rcp_f32_e32 v167, v167
	v_pk_mul_f32 v[80:81], v[80:81], v[162:163] op_sel_hi:[1,0]
	v_pk_mul_f32 v[82:83], v[82:83], v[162:163] op_sel_hi:[1,0]
	v_pk_mul_f32 v[80:81], v[80:81], v[164:165]
	v_pk_mul_f32 v[82:83], v[82:83], v[166:167]
	v_cvt_pk_bf16_f32 v172, v88, v89
	v_cvt_pk_bf16_f32 v173, v90, v91
	v_cvt_pk_bf16_f32 v174, v80, v81
	v_cvt_pk_bf16_f32 v175, v82, v83
	global_store_dwordx4 v168, v[172:175], s[100:101]
	v_fmamk_f32 v162, v251, 0x3a800000, v188
	v_rsq_f32_e32 v162, v162
	v_add_u32_e32 v168, 0x42000, v161
	s_nop 0
	v_mul_f32_e32 v170, 0xbfb8aa3b, v162
	v_mul_f32_e32 v162, v162, v162
	v_pk_mul_f32 v[164:165], v[72:73], v[170:171] op_sel_hi:[1,0]
	v_pk_mul_f32 v[166:167], v[74:75], v[170:171] op_sel_hi:[1,0]
	v_exp_f32_e32 v164, v164
	v_exp_f32_e32 v165, v165
	v_exp_f32_e32 v166, v166
	v_exp_f32_e32 v167, v167
	v_pk_mul_f32 v[72:73], v[72:73], v[76:77]
	v_pk_mul_f32 v[74:75], v[74:75], v[78:79]
	v_pk_add_f32 v[164:165], v[164:165], 1.0 op_sel_hi:[1,0]
	v_pk_add_f32 v[166:167], v[166:167], 1.0 op_sel_hi:[1,0]
	v_rcp_f32_e32 v164, v164
	v_rcp_f32_e32 v165, v165
	v_rcp_f32_e32 v166, v166
	v_rcp_f32_e32 v167, v167
	v_pk_mul_f32 v[72:73], v[72:73], v[162:163] op_sel_hi:[1,0]
	v_pk_mul_f32 v[74:75], v[74:75], v[162:163] op_sel_hi:[1,0]
	v_pk_mul_f32 v[72:73], v[72:73], v[164:165]
	v_pk_mul_f32 v[74:75], v[74:75], v[166:167]
	v_pk_mul_f32 v[164:165], v[64:65], v[170:171] op_sel_hi:[1,0]
	v_pk_mul_f32 v[166:167], v[66:67], v[170:171] op_sel_hi:[1,0]
	v_exp_f32_e32 v164, v164
	v_exp_f32_e32 v165, v165
	v_exp_f32_e32 v166, v166
	v_exp_f32_e32 v167, v167
	v_pk_mul_f32 v[64:65], v[64:65], v[68:69]
	v_pk_mul_f32 v[66:67], v[66:67], v[70:71]
	v_pk_add_f32 v[164:165], v[164:165], 1.0 op_sel_hi:[1,0]
	v_pk_add_f32 v[166:167], v[166:167], 1.0 op_sel_hi:[1,0]
	v_rcp_f32_e32 v164, v164
	v_rcp_f32_e32 v165, v165
	v_rcp_f32_e32 v166, v166
	v_rcp_f32_e32 v167, v167
	v_pk_mul_f32 v[64:65], v[64:65], v[162:163] op_sel_hi:[1,0]
	v_pk_mul_f32 v[66:67], v[66:67], v[162:163] op_sel_hi:[1,0]
	v_pk_mul_f32 v[64:65], v[64:65], v[164:165]
	v_pk_mul_f32 v[66:67], v[66:67], v[166:167]
	v_cvt_pk_bf16_f32 v176, v72, v73
	v_cvt_pk_bf16_f32 v177, v74, v75
	v_cvt_pk_bf16_f32 v178, v64, v65
	v_cvt_pk_bf16_f32 v179, v66, v67
	global_store_dwordx4 v168, v[176:179], s[100:101]
	v_fmamk_f32 v162, v252, 0x3a800000, v188
	v_rsq_f32_e32 v162, v162
	v_add_u32_e32 v168, 0xb0000, v161
	s_nop 0
	v_mul_f32_e32 v170, 0xbfb8aa3b, v162
	v_mul_f32_e32 v162, v162, v162
	v_pk_mul_f32 v[164:165], v[56:57], v[170:171] op_sel_hi:[1,0]
	v_pk_mul_f32 v[166:167], v[58:59], v[170:171] op_sel_hi:[1,0]
	v_exp_f32_e32 v164, v164
	v_exp_f32_e32 v165, v165
	v_exp_f32_e32 v166, v166
	v_exp_f32_e32 v167, v167
	v_pk_mul_f32 v[56:57], v[56:57], v[60:61]
	v_pk_mul_f32 v[58:59], v[58:59], v[62:63]
	v_pk_add_f32 v[164:165], v[164:165], 1.0 op_sel_hi:[1,0]
	v_pk_add_f32 v[166:167], v[166:167], 1.0 op_sel_hi:[1,0]
	v_rcp_f32_e32 v164, v164
	v_rcp_f32_e32 v165, v165
	v_rcp_f32_e32 v166, v166
	v_rcp_f32_e32 v167, v167
	v_pk_mul_f32 v[56:57], v[56:57], v[162:163] op_sel_hi:[1,0]
	v_pk_mul_f32 v[58:59], v[58:59], v[162:163] op_sel_hi:[1,0]
	v_pk_mul_f32 v[56:57], v[56:57], v[164:165]
	v_pk_mul_f32 v[58:59], v[58:59], v[166:167]
	v_pk_mul_f32 v[164:165], v[48:49], v[170:171] op_sel_hi:[1,0]
	v_pk_mul_f32 v[166:167], v[50:51], v[170:171] op_sel_hi:[1,0]
	v_exp_f32_e32 v164, v164
	v_exp_f32_e32 v165, v165
	v_exp_f32_e32 v166, v166
	v_exp_f32_e32 v167, v167
	v_pk_mul_f32 v[48:49], v[48:49], v[52:53]
	v_pk_mul_f32 v[50:51], v[50:51], v[54:55]
	v_pk_add_f32 v[164:165], v[164:165], 1.0 op_sel_hi:[1,0]
	v_pk_add_f32 v[166:167], v[166:167], 1.0 op_sel_hi:[1,0]
	v_rcp_f32_e32 v164, v164
	v_rcp_f32_e32 v165, v165
	v_rcp_f32_e32 v166, v166
	v_rcp_f32_e32 v167, v167
	v_pk_mul_f32 v[48:49], v[48:49], v[162:163] op_sel_hi:[1,0]
	v_pk_mul_f32 v[50:51], v[50:51], v[162:163] op_sel_hi:[1,0]
	v_pk_mul_f32 v[48:49], v[48:49], v[164:165]
	v_pk_mul_f32 v[50:51], v[50:51], v[166:167]
	v_cvt_pk_bf16_f32 v172, v56, v57
	v_cvt_pk_bf16_f32 v173, v58, v59
	v_cvt_pk_bf16_f32 v174, v48, v49
	v_cvt_pk_bf16_f32 v175, v50, v51
	global_store_dwordx4 v168, v[172:175], s[100:101]
	v_fmamk_f32 v162, v253, 0x3a800000, v188
	v_rsq_f32_e32 v162, v162
	v_add_u32_e32 v168, 0xc6000, v161
	s_nop 0
	v_mul_f32_e32 v170, 0xbfb8aa3b, v162
	v_mul_f32_e32 v162, v162, v162
	v_pk_mul_f32 v[164:165], v[40:41], v[170:171] op_sel_hi:[1,0]
	v_pk_mul_f32 v[166:167], v[42:43], v[170:171] op_sel_hi:[1,0]
	v_exp_f32_e32 v164, v164
	v_exp_f32_e32 v165, v165
	v_exp_f32_e32 v166, v166
	v_exp_f32_e32 v167, v167
	v_pk_mul_f32 v[40:41], v[40:41], v[44:45]
	v_pk_mul_f32 v[42:43], v[42:43], v[46:47]
	v_pk_add_f32 v[164:165], v[164:165], 1.0 op_sel_hi:[1,0]
	v_pk_add_f32 v[166:167], v[166:167], 1.0 op_sel_hi:[1,0]
	v_rcp_f32_e32 v164, v164
	v_rcp_f32_e32 v165, v165
	v_rcp_f32_e32 v166, v166
	v_rcp_f32_e32 v167, v167
; __device__ __forceinline__ float siluf_(float x) { return x * sigmoidf_(x); }
; __device__ __forceinline__ float rinv_of(float ssq) { return rsqrtf(ssq * (1.0f / 1024.0f) + EPS); }
; __device__ __forceinline__ u32x4 pack8(const f32x4 a, const f32x4 b) { u32x4 w; w.x = cvt_pk_bf16(a[0], a[1]); w.y = cvt_pk_bf16(a[2], a[3]); w.z = cvt_pk_bf16(b[0], b[1]); w.w = cvt_pk_bf16(b[2], b[3]); return w; }
; template <class Epi>
; __device__ __forceinline__ void gemm_phase(LAS unsigned char* lds, const Gemm g, const StaticOrder& S, const Epi& E) {
;     ...
;         if (!has_next) break;
; #pragma unroll
;         for (int a = 0; a < 2; ++a)
; #pragma unroll
;             for (int b = 0; b < 2; ++b)
; #pragma unroll
;                 for (int m = 0; m < 4; ++m)
; #pragma unroll
;                     for (int n = 0; n < 2; ++n) acc[a][b][m][n] = (f32x4){0.f, 0.f, 0.f, 0.f};
;         cur = nxt; cA = nA; cB = nB; ++ui;
;     __device__ __forceinline__ void operator()(const AccT& acc, const pg8::Unit& u, int wr, int wc, int fr, int fq) const {
;         asm volatile("" : "+v"(fr), "+v"(fq), "+s"(wr), "+s"(wc));
;         float ris[2][4];
; #pragma unroll
;         for (int ai = 0; ai < 2; ++ai)
; #pragma unroll
;             for (int m = 0; m < 4; ++m) ris[ai][m] = ssq_in[EPI_ROW(u, ai, m)];
; #pragma unroll
;         for (int ai = 0; ai < 2; ++ai)
; #pragma unroll
;             for (int m = 0; m < 4; ++m) {
;                 const int r = EPI_ROW(u, ai, m); const float ri = rinv_of(ris[ai][m]);
;                 f32x4 o[2];
; #pragma unroll
;                 for (int n = 0; n < 2; ++n) { const f32x4 gt = acc[ai][0][m][n] * ri, up = acc[ai][1][m][n] * ri;
; #pragma unroll
;                     for (int j = 0; j < 4; ++j) o[n][j] = siluf_(gt[j]) * up[j]; }
;                 *(u32x4*)(act + (size_t)r * DFF + u.pn * 128 + wc * 32 + 8 * fq) = pack8(o[0], o[1]); }
;     }
	v_pk_mul_f32 v[40:41], v[40:41], v[162:163] op_sel_hi:[1,0]
	v_pk_mul_f32 v[42:43], v[42:43], v[162:163] op_sel_hi:[1,0]
	v_pk_mul_f32 v[40:41], v[40:41], v[164:165]
	v_pk_mul_f32 v[42:43], v[42:43], v[166:167]
	v_pk_mul_f32 v[164:165], v[32:33], v[170:171] op_sel_hi:[1,0]
	v_pk_mul_f32 v[166:167], v[34:35], v[170:171] op_sel_hi:[1,0]
	v_exp_f32_e32 v164, v164
	v_exp_f32_e32 v165, v165
	v_exp_f32_e32 v166, v166
	v_exp_f32_e32 v167, v167
	v_pk_mul_f32 v[32:33], v[32:33], v[36:37]
	v_pk_mul_f32 v[34:35], v[34:35], v[38:39]
	v_pk_add_f32 v[164:165], v[164:165], 1.0 op_sel_hi:[1,0]
	v_pk_add_f32 v[166:167], v[166:167], 1.0 op_sel_hi:[1,0]
	v_rcp_f32_e32 v164, v164
	v_rcp_f32_e32 v165, v165
	v_rcp_f32_e32 v166, v166
	v_rcp_f32_e32 v167, v167
	v_pk_mul_f32 v[32:33], v[32:33], v[162:163] op_sel_hi:[1,0]
	v_pk_mul_f32 v[34:35], v[34:35], v[162:163] op_sel_hi:[1,0]
	v_pk_mul_f32 v[32:33], v[32:33], v[164:165]
	v_pk_mul_f32 v[34:35], v[34:35], v[166:167]
	v_cvt_pk_bf16_f32 v176, v40, v41
	v_cvt_pk_bf16_f32 v177, v42, v43
	v_cvt_pk_bf16_f32 v178, v32, v33
	v_cvt_pk_bf16_f32 v179, v34, v35
	global_store_dwordx4 v168, v[176:179], s[100:101]
	v_fmamk_f32 v162, v254, 0x3a800000, v188
	v_rsq_f32_e32 v162, v162
	v_add_u32_e32 v168, 0xdc000, v161
	s_nop 0
	v_mul_f32_e32 v170, 0xbfb8aa3b, v162
	v_mul_f32_e32 v162, v162, v162
	v_pk_mul_f32 v[164:165], v[24:25], v[170:171] op_sel_hi:[1,0]
	v_pk_mul_f32 v[166:167], v[26:27], v[170:171] op_sel_hi:[1,0]
	v_exp_f32_e32 v164, v164
	v_exp_f32_e32 v165, v165
	v_exp_f32_e32 v166, v166
	v_exp_f32_e32 v167, v167
	v_pk_mul_f32 v[24:25], v[24:25], v[28:29]
	v_pk_mul_f32 v[26:27], v[26:27], v[30:31]
	v_pk_add_f32 v[164:165], v[164:165], 1.0 op_sel_hi:[1,0]
	v_pk_add_f32 v[166:167], v[166:167], 1.0 op_sel_hi:[1,0]
	v_rcp_f32_e32 v164, v164
	v_rcp_f32_e32 v165, v165
	v_rcp_f32_e32 v166, v166
	v_rcp_f32_e32 v167, v167
	v_pk_mul_f32 v[24:25], v[24:25], v[162:163] op_sel_hi:[1,0]
	v_pk_mul_f32 v[26:27], v[26:27], v[162:163] op_sel_hi:[1,0]
	v_pk_mul_f32 v[24:25], v[24:25], v[164:165]
	v_pk_mul_f32 v[26:27], v[26:27], v[166:167]
	v_pk_mul_f32 v[164:165], v[16:17], v[170:171] op_sel_hi:[1,0]
	v_pk_mul_f32 v[166:167], v[18:19], v[170:171] op_sel_hi:[1,0]
	v_exp_f32_e32 v164, v164
	v_exp_f32_e32 v165, v165
	v_exp_f32_e32 v166, v166
	v_exp_f32_e32 v167, v167
	v_pk_mul_f32 v[16:17], v[16:17], v[20:21]
	v_pk_mul_f32 v[18:19], v[18:19], v[22:23]
	v_pk_add_f32 v[164:165], v[164:165], 1.0 op_sel_hi:[1,0]
	v_pk_add_f32 v[166:167], v[166:167], 1.0 op_sel_hi:[1,0]
	v_rcp_f32_e32 v164, v164
	v_rcp_f32_e32 v165, v165
	v_rcp_f32_e32 v166, v166
	v_rcp_f32_e32 v167, v167
	v_pk_mul_f32 v[16:17], v[16:17], v[162:163] op_sel_hi:[1,0]
	v_pk_mul_f32 v[18:19], v[18:19], v[162:163] op_sel_hi:[1,0]
	v_pk_mul_f32 v[16:17], v[16:17], v[164:165]
	v_pk_mul_f32 v[18:19], v[18:19], v[166:167]
	v_cvt_pk_bf16_f32 v172, v24, v25
	v_cvt_pk_bf16_f32 v173, v26, v27
	v_cvt_pk_bf16_f32 v174, v16, v17
	v_cvt_pk_bf16_f32 v175, v18, v19
	global_store_dwordx4 v168, v[172:175], s[100:101]
	v_fmamk_f32 v162, v255, 0x3a800000, v188
	v_rsq_f32_e32 v162, v162
	v_add_u32_e32 v168, 0xf2000, v161
	s_nop 0
	v_mul_f32_e32 v170, 0xbfb8aa3b, v162
	v_mul_f32_e32 v162, v162, v162
	v_pk_mul_f32 v[164:165], v[8:9], v[170:171] op_sel_hi:[1,0]
	v_pk_mul_f32 v[166:167], v[10:11], v[170:171] op_sel_hi:[1,0]
	v_exp_f32_e32 v164, v164
	v_exp_f32_e32 v165, v165
	v_exp_f32_e32 v166, v166
	v_exp_f32_e32 v167, v167
	v_pk_mul_f32 v[8:9], v[8:9], v[12:13]
	v_pk_mul_f32 v[10:11], v[10:11], v[14:15]
	v_pk_add_f32 v[164:165], v[164:165], 1.0 op_sel_hi:[1,0]
	v_pk_add_f32 v[166:167], v[166:167], 1.0 op_sel_hi:[1,0]
	v_rcp_f32_e32 v164, v164
	v_rcp_f32_e32 v165, v165
	v_rcp_f32_e32 v166, v166
	v_rcp_f32_e32 v167, v167
	v_pk_mul_f32 v[8:9], v[8:9], v[162:163] op_sel_hi:[1,0]
	v_pk_mul_f32 v[10:11], v[10:11], v[162:163] op_sel_hi:[1,0]
	v_pk_mul_f32 v[8:9], v[8:9], v[164:165]
	v_pk_mul_f32 v[10:11], v[10:11], v[166:167]
	v_pk_mul_f32 v[164:165], v[4:5], v[170:171] op_sel_hi:[1,0]
	v_pk_mul_f32 v[166:167], v[6:7], v[170:171] op_sel_hi:[1,0]
	v_exp_f32_e32 v164, v164
	v_exp_f32_e32 v165, v165
	v_exp_f32_e32 v166, v166
	v_exp_f32_e32 v167, v167
	v_pk_mul_f32 v[4:5], v[4:5], v[0:1]
	v_pk_mul_f32 v[6:7], v[6:7], v[2:3]
	v_pk_add_f32 v[164:165], v[164:165], 1.0 op_sel_hi:[1,0]
	v_pk_add_f32 v[166:167], v[166:167], 1.0 op_sel_hi:[1,0]
	v_rcp_f32_e32 v164, v164
	v_rcp_f32_e32 v165, v165
	v_rcp_f32_e32 v166, v166
	v_rcp_f32_e32 v167, v167
	v_pk_mul_f32 v[4:5], v[4:5], v[162:163] op_sel_hi:[1,0]
	v_pk_mul_f32 v[6:7], v[6:7], v[162:163] op_sel_hi:[1,0]
	v_pk_mul_f32 v[4:5], v[4:5], v[164:165]
	v_pk_mul_f32 v[6:7], v[6:7], v[166:167]
	v_cvt_pk_bf16_f32 v176, v8, v9
	v_cvt_pk_bf16_f32 v177, v10, v11
	v_cvt_pk_bf16_f32 v178, v4, v5
	v_cvt_pk_bf16_f32 v179, v6, v7
	global_store_dwordx4 v168, v[176:179], s[100:101]
	s_mov_b64 s[28:29], s[20:21]
	s_mov_b32 s25, s16
	s_mov_b32 s24, s18
	s_mov_b64 s[26:27], s[22:23]
	s_and_b64 vcc, exec, s[6:7]
	s_cbranch_vccnz .LBB0_2412
